# final: P9/P7 row-scale loads pre-issued before the K-loop, P4 Q/K epilogue loads batched (waits kept), P11 row loads batched, P0 rms gain loads hoisted; 8 wait states kept between stores and rewrites
# baseline (speedup 1.0000x reference)
.LBB0_89:
	global_load_dwordx4 v[32:35], v[24:25], off offset:-3072 nt
	global_load_dwordx4 v[36:39], v[24:25], off offset:-2048 nt
	global_load_dwordx4 v[6:9], v[24:25], off nt
	global_load_dwordx4 v[40:43], v[24:25], off offset:-1024 nt
	v_add_co_u32_e32 v60, vcc, 0xfffff000, v24
	s_add_i32 s8, s8, s82
	s_nop 0
	v_addc_co_u32_e32 v61, vcc, -1, v25, vcc
	global_load_dwordx4 v[44:47], v[60:61], off offset:-3072 nt
	global_load_dwordx4 v[48:51], v[60:61], off offset:-2048 nt
	global_load_dwordx4 v[52:55], v[60:61], off offset:-1024 nt
	global_load_dwordx4 v[56:59], v[24:25], off offset:-4096 nt
	s_cmpk_gt_i32 s8, 0x7fff
	v_lshl_add_u64 v[24:25], v[24:25], 0, s[6:7]
	s_waitcnt vmcnt(7)
	v_mul_f32_e32 v83, v32, v32
	s_waitcnt vmcnt(6)
	v_pk_mul_f32 v[60:61], v[38:39], v[38:39]
	v_pk_mul_f32 v[62:63], v[36:37], v[36:37]
	s_waitcnt vmcnt(4)
	v_mul_f32_e32 v64, v41, v41
	v_mul_f32_e32 v66, v43, v43
	v_mul_f32_e32 v81, v8, v8
	v_mul_f32_e32 v89, v9, v9
	v_pk_mov_b32 v[68:69], v[62:63], v[60:61] op_sel:[1,0]
	v_mov_b32_e32 v63, v61
	v_pk_fma_f32 v[60:61], v[40:41], v[40:41], v[64:65] op_sel_hi:[1,1,0]
	v_pk_fma_f32 v[64:65], v[42:43], v[42:43], v[66:67] op_sel_hi:[1,1,0]
	s_waitcnt vmcnt(3)
	v_mov_b32_e32 v70, v45
	s_waitcnt vmcnt(2)
	v_mov_b32_e32 v71, v49
	v_mov_b32_e32 v74, v47
	v_mov_b32_e32 v75, v51
	v_mov_b32_e32 v66, v44
	v_mov_b32_e32 v67, v48
	v_mov_b32_e32 v72, v46
	v_mov_b32_e32 v73, v50
	s_waitcnt vmcnt(1)
	v_pk_mul_f32 v[76:77], v[54:55], v[54:55]
	v_pk_mul_f32 v[78:79], v[52:53], v[52:53]
	v_pk_add_f32 v[62:63], v[68:69], v[62:63]
	v_mov_b32_e32 v61, v81
	v_mov_b32_e32 v65, v89
	v_pk_mul_f32 v[68:69], v[70:71], v[70:71]
	v_pk_mul_f32 v[70:71], v[74:75], v[74:75]
	v_pk_mov_b32 v[74:75], v[78:79], v[76:77] op_sel:[1,0]
	v_mov_b32_e32 v79, v77
	v_pk_add_f32 v[60:61], v[60:61], v[64:65]
	v_pk_fma_f32 v[64:65], v[66:67], v[66:67], v[68:69]
	v_pk_fma_f32 v[66:67], v[72:73], v[72:73], v[70:71]
	s_waitcnt vmcnt(0)
	v_mul_f32_e32 v80, v57, v57
	v_mul_f32_e32 v82, v59, v59
	v_pk_add_f32 v[68:69], v[74:75], v[78:79]
	v_pk_add_f32 v[64:65], v[64:65], v[66:67]
	v_mul_f32_e32 v84, v33, v33
	v_mul_f32_e32 v85, v34, v34
	v_mul_f32_e32 v86, v35, v35
	v_pk_fma_f32 v[76:77], v[56:57], v[56:57], v[80:81] op_sel_hi:[1,1,0]
	v_pk_fma_f32 v[80:81], v[58:59], v[58:59], v[82:83] op_sel_hi:[1,1,0]
	v_pk_add_f32 v[66:67], v[68:69], v[68:69] op_sel:[0,1] op_sel_hi:[1,0]
	v_pk_add_f32 v[64:65], v[64:65], v[64:65] op_sel:[0,1] op_sel_hi:[1,0]
	v_mov_b32_e32 v77, v85
	v_mov_b32_e32 v81, v86
	v_mov_b32_e32 v67, v84
	v_mov_b32_e32 v65, v83
	v_pk_add_f32 v[68:69], v[76:77], v[80:81]
	v_pk_add_f32 v[64:65], v[64:65], v[66:67]
	v_mul_f32_e32 v87, v6, v6
	v_pk_add_f32 v[64:65], v[64:65], v[68:69]
	v_mul_f32_e32 v88, v7, v7
	v_pk_add_f32 v[62:63], v[62:63], v[62:63] op_sel:[0,1] op_sel_hi:[1,0]
	v_pk_add_f32 v[64:65], v[64:65], v[64:65] op_sel:[0,1] op_sel_hi:[1,0]
	v_mov_b32_e32 v63, v88
	v_mov_b32_e32 v65, v87
	v_pk_add_f32 v[62:63], v[64:65], v[62:63]
	s_nop 0
	v_pk_add_f32 v[60:61], v[62:63], v[60:61]
	s_nop 0
	v_add_f32_e32 v60, v60, v61
	ds_bpermute_b32 v61, v26, v60
	s_waitcnt lgkmcnt(0)
	v_add_f32_e32 v60, v60, v61
	ds_bpermute_b32 v61, v27, v60
	s_waitcnt lgkmcnt(0)
	v_add_f32_e32 v60, v60, v61
	ds_bpermute_b32 v61, v28, v60
	s_waitcnt lgkmcnt(0)
	v_add_f32_e32 v60, v60, v61
	ds_bpermute_b32 v61, v29, v60
	s_waitcnt lgkmcnt(0)
	v_add_f32_e32 v60, v60, v61
	ds_bpermute_b32 v61, v30, v60
	s_waitcnt lgkmcnt(0)
	v_add_f32_e32 v60, v60, v61
	ds_bpermute_b32 v61, v31, v60
	s_waitcnt lgkmcnt(0)
	v_add_f32_e32 v60, v60, v61
	v_fmamk_f32 v60, v60, 0x3a000000, v11
	v_mul_f32_e32 v61, 0x4b800000, v60
	v_cmp_gt_f32_e32 vcc, s3, v60
	s_nop 1
	v_cndmask_b32_e32 v60, v60, v61, vcc
	v_rsq_f32_e32 v60, v60
	s_nop 0
	v_mul_f32_e32 v61, 0x45800000, v60
	v_cndmask_b32_e32 v62, v60, v61, vcc
	v_mul_f32_e32 v44, v44, v62
	v_mul_f32_e32 v45, v45, v62
	v_mul_f32_e32 v46, v46, v62
	v_mul_f32_e32 v47, v47, v62
	v_mul_f32_e32 v44, v2, v44
	v_mul_f32_e32 v45, v3, v45
	v_mul_f32_e32 v46, v4, v46
	v_mul_f32_e32 v47, v5, v47
	v_cvt_pk_bf16_f32 v60, v44, v45
	v_cvt_pk_bf16_f32 v61, v46, v47
	v_mov_b64_e32 v[44:45], v[96:97]
	v_mov_b64_e32 v[46:47], v[98:99]
	v_mul_f32_e32 v48, v48, v62
	v_mul_f32_e32 v49, v49, v62
	v_mul_f32_e32 v50, v50, v62
	v_mul_f32_e32 v51, v51, v62
	global_store_dwordx2 v[22:23], v[60:61], off offset:-3584
	v_mul_f32_e32 v32, v32, v62
	v_mul_f32_e32 v33, v33, v62
	v_mul_f32_e32 v34, v34, v62
	v_mul_f32_e32 v35, v35, v62
	v_mul_f32_e32 v36, v36, v62
	v_mul_f32_e32 v37, v37, v62
	v_mul_f32_e32 v38, v38, v62
	v_mul_f32_e32 v39, v39, v62
	v_mul_f32_e32 v6, v6, v62
	v_mul_f32_e32 v7, v7, v62
	v_mul_f32_e32 v8, v8, v62
	v_mul_f32_e32 v9, v9, v62
	s_nop 7
	v_mul_f32_e32 v44, v44, v48
	v_mul_f32_e32 v45, v45, v49
	v_mul_f32_e32 v46, v46, v50
	v_mul_f32_e32 v47, v47, v51
	v_cvt_pk_bf16_f32 v48, v44, v45
	v_cvt_pk_bf16_f32 v49, v46, v47
	v_mov_b64_e32 v[44:45], v[100:101]
	v_mov_b64_e32 v[46:47], v[102:103]
	v_mul_f32_e32 v50, v52, v62
	v_mul_f32_e32 v51, v53, v62
	v_mul_f32_e32 v52, v54, v62
	v_mul_f32_e32 v53, v55, v62
	global_store_dwordx2 v[22:23], v[48:49], off offset:-3072
	s_nop 7
	v_mul_f32_e32 v44, v44, v50
	v_mul_f32_e32 v45, v45, v51
	v_mul_f32_e32 v46, v46, v52
	v_mul_f32_e32 v47, v47, v53
	v_cvt_pk_bf16_f32 v48, v44, v45
	v_cvt_pk_bf16_f32 v49, v46, v47
	v_mov_b64_e32 v[44:45], v[104:105]
	v_mov_b64_e32 v[46:47], v[106:107]
	v_mul_f32_e32 v50, v56, v62
	v_mul_f32_e32 v51, v57, v62
	v_mul_f32_e32 v52, v58, v62
	v_mul_f32_e32 v53, v59, v62
	global_store_dwordx2 v[22:23], v[48:49], off offset:-2560
	s_nop 7
	v_mul_f32_e32 v44, v50, v44
	v_mul_f32_e32 v45, v51, v45
	v_mul_f32_e32 v46, v52, v46
	v_mul_f32_e32 v47, v53, v47
	v_cvt_pk_bf16_f32 v48, v44, v45
	v_cvt_pk_bf16_f32 v49, v46, v47
	v_mov_b64_e32 v[44:45], v[108:109]
	v_mov_b64_e32 v[46:47], v[110:111]
	s_nop 7
	v_mul_f32_e32 v32, v32, v44
	v_mul_f32_e32 v33, v33, v45
	v_mul_f32_e32 v34, v34, v46
	v_mul_f32_e32 v35, v35, v47
	global_store_dwordx2 v[22:23], v[48:49], off offset:-2048
	v_cvt_pk_bf16_f32 v44, v32, v33
	v_cvt_pk_bf16_f32 v45, v34, v35
	v_mov_b64_e32 v[32:33], v[112:113]
	v_mov_b64_e32 v[34:35], v[114:115]
	s_nop 7
	v_mul_f32_e32 v32, v36, v32
	v_mul_f32_e32 v33, v37, v33
	v_mul_f32_e32 v34, v38, v34
	v_mul_f32_e32 v35, v39, v35
	global_store_dwordx2 v[22:23], v[44:45], off offset:-1536
	v_cvt_pk_bf16_f32 v36, v32, v33
	v_cvt_pk_bf16_f32 v37, v34, v35
	v_mov_b64_e32 v[32:33], v[116:117]
	v_mov_b64_e32 v[34:35], v[118:119]
	v_mul_f32_e32 v38, v40, v62
	v_mul_f32_e32 v39, v41, v62
	v_mul_f32_e32 v40, v42, v62
	v_mul_f32_e32 v41, v43, v62
	global_store_dwordx2 v[22:23], v[36:37], off offset:-1024
	s_nop 7
	v_mul_f32_e32 v32, v38, v32
	v_mul_f32_e32 v33, v39, v33
	v_mul_f32_e32 v34, v40, v34
	v_mul_f32_e32 v35, v41, v35
	v_cvt_pk_bf16_f32 v36, v32, v33
	v_cvt_pk_bf16_f32 v37, v34, v35
	v_mov_b64_e32 v[32:33], v[120:121]
	v_mov_b64_e32 v[34:35], v[122:123]
	s_nop 7
	v_mul_f32_e32 v6, v6, v32
	v_mul_f32_e32 v7, v7, v33
	global_store_dwordx2 v[22:23], v[36:37], off offset:-512
	v_mul_f32_e32 v8, v8, v34
	v_mul_f32_e32 v9, v9, v35
	v_cvt_pk_bf16_f32 v6, v6, v7
	v_cvt_pk_bf16_f32 v7, v8, v9
	global_store_dwordx2 v[22:23], v[6:7], off
	v_lshl_add_u64 v[22:23], v[22:23], 0, s[0:1]
	s_cbranch_scc0 .LBB0_89
